# grid barrier: XCD leader poll issues its 16 counter loads back to back, single wait, then sums (was 7 chained round trips)
# speedup vs baseline: 1.0150x; 1.0037x over previous
.LBB0_414:
	s_mov_b64 s[4:5], -1
	s_waitcnt lgkmcnt(0)
	v_readlane_b32 s2, v254, 25
	v_readlane_b32 s3, v254, 26
	s_nop 4
	global_load_dword v0, v33, s[2:3] sc1
	v_readlane_b32 s2, v254, 27
	v_readlane_b32 s3, v254, 28
	s_nop 4
	global_load_dword v1, v33, s[2:3] sc1
	v_readlane_b32 s2, v254, 29
	v_readlane_b32 s3, v254, 30
	s_nop 4
	global_load_dword v2, v33, s[2:3] sc1
	v_readlane_b32 s2, v254, 31
	v_readlane_b32 s3, v254, 32
	s_nop 4
	global_load_dword v3, v33, s[2:3] sc1
	v_readlane_b32 s2, v254, 33
	v_readlane_b32 s3, v254, 34
	s_nop 4
	global_load_dword v4, v33, s[2:3] sc1
	v_readlane_b32 s2, v254, 35
	v_readlane_b32 s3, v254, 36
	s_nop 4
	global_load_dword v5, v33, s[2:3] sc1
	v_readlane_b32 s2, v254, 37
	v_readlane_b32 s3, v254, 38
	s_nop 4
	global_load_dword v6, v33, s[2:3] sc1
	v_readlane_b32 s2, v254, 39
	v_readlane_b32 s3, v254, 40
	s_nop 4
	global_load_dword v7, v33, s[2:3] sc1
	global_load_dword v8, v33, s[68:69] sc1
	global_load_dword v9, v33, s[70:71] sc1
	global_load_dword v10, v33, s[72:73] sc1
	global_load_dword v11, v33, s[74:75] sc1
	global_load_dword v12, v33, s[76:77] sc1
	global_load_dword v13, v33, s[78:79] sc1
	global_load_dword v14, v33, s[80:81] sc1
	global_load_dword v15, v33, s[82:83] sc1
	s_mov_b64 s[2:3], -1
	s_waitcnt vmcnt(0)
	v_add_u32_e32 v16, v1, v0
	v_add_u32_e32 v16, v16, v2
	v_add_u32_e32 v16, v16, v3
	v_add_u32_e32 v16, v16, v4
	v_add_u32_e32 v16, v16, v5
	v_add_u32_e32 v16, v16, v6
	v_add_u32_e32 v16, v16, v7
	v_add_u32_e32 v16, v16, v8
	v_add_u32_e32 v16, v16, v9
	v_add_u32_e32 v16, v16, v10
	v_add_u32_e32 v16, v16, v11
	v_add_u32_e32 v16, v16, v12
	v_add_u32_e32 v16, v16, v13
	v_add_u32_e32 v16, v16, v14
	v_add_u32_e32 v16, v16, v15
	v_cmp_eq_u32_e32 vcc, s29, v16
	s_cbranch_vccnz .LBB0_413
	s_and_b32 s2, s9, 0xff
	s_cmp_eq_u32 s2, 0
	s_mov_b64 s[2:3], -1
	s_mov_b64 s[6:7], -1
	s_sleep 1
	s_cbranch_scc0 .LBB0_418
	v_readlane_b32 s2, v254, 41
	v_readlane_b32 s3, v254, 42
	s_nop 4
	global_load_dword v16, v33, s[2:3] sc1
	s_waitcnt vmcnt(0)
	v_cmp_eq_u32_e32 vcc, 0, v16
	s_cbranch_vccnz .LBB0_420
	s_mov_b64 s[6:7], 0
	s_mov_b64 s[2:3], -1

.LBB0_637:
	s_mov_b64 s[6:7], -1
	s_waitcnt lgkmcnt(0)
	v_readlane_b32 s4, v254, 25
	v_readlane_b32 s5, v254, 26
	s_nop 4
	global_load_dword v0, v33, s[4:5] sc1
	v_readlane_b32 s4, v254, 27
	v_readlane_b32 s5, v254, 28
	s_nop 4
	global_load_dword v1, v33, s[4:5] sc1
	v_readlane_b32 s4, v254, 29
	v_readlane_b32 s5, v254, 30
	s_nop 4
	global_load_dword v2, v33, s[4:5] sc1
	v_readlane_b32 s4, v254, 31
	v_readlane_b32 s5, v254, 32
	s_nop 4
	global_load_dword v3, v33, s[4:5] sc1
	v_readlane_b32 s4, v254, 33
	v_readlane_b32 s5, v254, 34
	s_nop 4
	global_load_dword v4, v33, s[4:5] sc1
	v_readlane_b32 s4, v254, 35
	v_readlane_b32 s5, v254, 36
	s_nop 4
	global_load_dword v5, v33, s[4:5] sc1
	v_readlane_b32 s4, v254, 37
	v_readlane_b32 s5, v254, 38
	s_nop 4
	global_load_dword v6, v33, s[4:5] sc1
	v_readlane_b32 s4, v254, 39
	v_readlane_b32 s5, v254, 40
	s_nop 4
	global_load_dword v7, v33, s[4:5] sc1
	global_load_dword v8, v33, s[68:69] sc1
	global_load_dword v9, v33, s[70:71] sc1
	global_load_dword v10, v33, s[72:73] sc1
	global_load_dword v11, v33, s[74:75] sc1
	global_load_dword v12, v33, s[76:77] sc1
	global_load_dword v13, v33, s[78:79] sc1
	global_load_dword v14, v33, s[80:81] sc1
	global_load_dword v15, v33, s[82:83] sc1
	s_mov_b64 s[4:5], -1
	s_waitcnt vmcnt(0)
	v_add_u32_e32 v16, v1, v0
	v_add_u32_e32 v16, v16, v2
	v_add_u32_e32 v16, v16, v3
	v_add_u32_e32 v16, v16, v4
	v_add_u32_e32 v16, v16, v5
	v_add_u32_e32 v16, v16, v6
	v_add_u32_e32 v16, v16, v7
	v_add_u32_e32 v16, v16, v8
	v_add_u32_e32 v16, v16, v9
	v_add_u32_e32 v16, v16, v10
	v_add_u32_e32 v16, v16, v11
	v_add_u32_e32 v16, v16, v12
	v_add_u32_e32 v16, v16, v13
	v_add_u32_e32 v16, v16, v14
	v_add_u32_e32 v16, v16, v15
	v_cmp_eq_u32_e32 vcc, s29, v16
	s_cbranch_vccnz .LBB0_636
	s_and_b32 s4, s11, 0xff
	s_cmp_eq_u32 s4, 0
	s_mov_b64 s[4:5], -1
	s_mov_b64 s[8:9], -1
	s_sleep 1
	s_cbranch_scc0 .LBB0_641
	v_readlane_b32 s4, v254, 41
	v_readlane_b32 s5, v254, 42
	s_nop 4
	global_load_dword v16, v33, s[4:5] sc1
	s_waitcnt vmcnt(0)
	v_cmp_eq_u32_e32 vcc, 0, v16
	s_cbranch_vccnz .LBB0_643
	s_mov_b64 s[8:9], 0
	s_mov_b64 s[4:5], -1

.LBB0_732:
	s_mov_b64 s[6:7], -1
	s_waitcnt lgkmcnt(0)
	v_readlane_b32 s2, v254, 25
	v_readlane_b32 s3, v254, 26
	s_nop 4
	global_load_dword v0, v33, s[2:3] sc1
	v_readlane_b32 s2, v254, 27
	v_readlane_b32 s3, v254, 28
	s_nop 4
	global_load_dword v1, v33, s[2:3] sc1
	v_readlane_b32 s2, v254, 29
	v_readlane_b32 s3, v254, 30
	s_nop 4
	global_load_dword v2, v33, s[2:3] sc1
	v_readlane_b32 s2, v254, 31
	v_readlane_b32 s3, v254, 32
	s_nop 4
	global_load_dword v3, v33, s[2:3] sc1
	v_readlane_b32 s2, v254, 33
	v_readlane_b32 s3, v254, 34
	s_nop 4
	global_load_dword v4, v33, s[2:3] sc1
	v_readlane_b32 s2, v254, 35
	v_readlane_b32 s3, v254, 36
	s_nop 4
	global_load_dword v5, v33, s[2:3] sc1
	v_readlane_b32 s2, v254, 37
	v_readlane_b32 s3, v254, 38
	s_nop 4
	global_load_dword v6, v33, s[2:3] sc1
	v_readlane_b32 s2, v254, 39
	v_readlane_b32 s3, v254, 40
	s_nop 4
	global_load_dword v7, v33, s[2:3] sc1
	global_load_dword v8, v33, s[68:69] sc1
	global_load_dword v9, v33, s[70:71] sc1
	global_load_dword v10, v33, s[72:73] sc1
	global_load_dword v11, v33, s[74:75] sc1
	global_load_dword v12, v33, s[76:77] sc1
	global_load_dword v13, v33, s[78:79] sc1
	global_load_dword v14, v33, s[80:81] sc1
	global_load_dword v15, v33, s[82:83] sc1
	s_mov_b64 s[2:3], -1
	s_waitcnt vmcnt(0)
	v_add_u32_e32 v16, v1, v0
	v_add_u32_e32 v16, v16, v2
	v_add_u32_e32 v16, v16, v3
	v_add_u32_e32 v16, v16, v4
	v_add_u32_e32 v16, v16, v5
	v_add_u32_e32 v16, v16, v6
	v_add_u32_e32 v16, v16, v7
	v_add_u32_e32 v16, v16, v8
	v_add_u32_e32 v16, v16, v9
	v_add_u32_e32 v16, v16, v10
	v_add_u32_e32 v16, v16, v11
	v_add_u32_e32 v16, v16, v12
	v_add_u32_e32 v16, v16, v13
	v_add_u32_e32 v16, v16, v14
	v_add_u32_e32 v16, v16, v15
	v_cmp_eq_u32_e32 vcc, s29, v16
	s_cbranch_vccnz .LBB0_731
	s_and_b32 s2, s11, 0xff
	s_cmp_eq_u32 s2, 0
	s_mov_b64 s[2:3], -1
	s_mov_b64 s[8:9], -1
	s_sleep 1
	s_cbranch_scc0 .LBB0_736
	v_readlane_b32 s2, v254, 41
	v_readlane_b32 s3, v254, 42
	s_nop 4
	global_load_dword v16, v33, s[2:3] sc1
	s_waitcnt vmcnt(0)
	v_cmp_eq_u32_e32 vcc, 0, v16
	s_cbranch_vccnz .LBB0_738
	s_mov_b64 s[8:9], 0
	s_mov_b64 s[2:3], -1
